# speedup vs baseline: 1.0013x; 1.0013x over previous
; __device__ __forceinline__ void p0_transpose_item(const float* W, int K, int N, const float* gain, const float* gain2  , bf16_t* WT, LAS unsigned* scr, int item, int lane) {
;     const int nblk = N / 64, kb = item / nblk, nb = item % nblk, k0 = 64 * kb, n0 = 64 * nb;
;     if (gain2 && k0 >= 1024) gain = gain2 - 1024;
;     const int n4 = lane & 15, kq = lane >> 4;
;     f32x4 r0[8], r1[8];
;     const float* src = W + (size_t)(k0 + 2 * kq) * N + n0 + 4 * n4;
; #pragma unroll
;     for (int j = 0; j < 8; ++j) { r0[j] = __builtin_nontemporal_load((const f32x4*)(src + (size_t)(8 * j) * N)); r1[j] = __builtin_nontemporal_load((const f32x4*)(src + (size_t)(8 * j + 1) * N)); }
; #pragma unroll
;     for (int j = 0; j < 8; ++j) {
;         float g0 = 1.f, g1 = 1.f; if (gain) { g0 = gain[k0 + 8 * j + 2 * kq]; g1 = gain[k0 + 8 * j + 2 * kq + 1]; }
; #pragma unroll
;         for (int i = 0; i < 4; ++i) scr[(4 * n4 + i) * 32 + (((j ^ (n4 & 7)) << 2) | kq)] = pk2(r0[j][i] * g0, r1[j][i] * g1);
;     }
; __device__ __forceinline__ void p0_prologue(const Params& p, LAS unsigned char* lds, int tid) {
;     ...
;     constexpr int I_IN = (DM / 64) * (INW / 64), I_GLU = (1024 / 64) * (1024 / 64), I_OUT = (DM / 64) * (DM / 64), I_UP = (DM / 64) * (DFF / 64), I_DN = (DFF / 64) * (DM / 64);
;     constexpr int I_LAYER = I_IN + I_GLU + I_OUT + I_UP + I_DN;
;     for (int it = gw; it < I_LAYER * DEPTH; it += NGW) {
;         const int l = it / I_LAYER; int r = it % I_LAYER;
;         unsigned char* wl = p.ws + (size_t)l * LAYER_BYTES;
;         if (r < I_IN) { p0_transpose_item(p.in[3] + (size_t)l * DM * INW, DM, INW, p.in[2] + l * DM, nullptr, (bf16_t*)(wl + LO_WIN), scr, r, lane); continue; } r -= I_IN;
;         if (r < I_UP) { p0_transpose_item(p.in[21] + (size_t)l * DM * DFF, DM, DFF, p.in[20] + l * DM, nullptr, (bf16_t*)(wl + LO_WUP), scr, r, lane); continue; } r -= I_UP;
;         if (r < I_DN) { p0_transpose_item(p.in[22] + (size_t)l * DFF * DM, DFF, DM, nullptr, nullptr, (bf16_t*)(wl + LO_WDN), scr, r, lane); continue; } r -= I_DN;
;         if (r < I_GLU) { p0_transpose_item(p.in[15] + (size_t)l * 1024 * 1024, 1024, 1024, nullptr, nullptr, (bf16_t*)(wl + LO_WGLU), scr, r, lane); continue; } r -= I_GLU;
;         p0_transpose_item(p.in[19] + (size_t)l * DM * DM, DM, DM, p.in[17] + l * 1024, p.in[18] + l * 1024, (bf16_t*)(wl + LO_WOUT), scr, r, lane);
;     }
.LBB0_114:
	v_writelane_b32 v253, s2, 34
	s_or_b64 exec, exec, s[12:13]
	s_movk_i32 s0, 0xd00
	v_cmp_gt_i32_e32 vcc, s0, v66
	s_and_saveexec_b64 s[4:5], vcc
	s_cbranch_execz .LBB0_181
	v_lshl_add_u32 v3, v11, 13, 0
	v_lshrrev_b32_e32 v4, 4, v10
	v_lshlrev_b32_e32 v7, 4, v201
	v_lshl_add_u32 v6, v4, 2, v3
	v_and_b32_e32 v7, 0x70, v7
	s_movk_i32 s1, 0x50
	v_lshlrev_b32_e32 v5, 2, v10
	s_movk_i32 s0, 0x70
	v_xad_u32 v91, v7, s1, v6
	s_movk_i32 s1, 0x60
	v_lshrrev_b32_e32 v94, 3, v10
	v_add_u32_e32 v71, v6, v7
	v_xad_u32 v87, v7, 16, v6
	v_xad_u32 v88, v7, 32, v6
	v_xad_u32 v89, v7, 48, v6
	v_xad_u32 v90, v7, 64, v6
	v_xad_u32 v92, v7, s1, v6
	v_xad_u32 v93, v7, s0, v6
	v_bitop3_b32 v7, v94, 28, v5 bitop3:0x48
	v_or_b32_e32 v96, 8, v94
	v_lshlrev_b32_e32 v6, 7, v94
	v_lshlrev_b32_e32 v7, 2, v7
	v_bitop3_b32 v8, v96, 28, v5 bitop3:0x48
	v_add3_u32 v95, v3, v6, v7
	v_lshlrev_b32_e32 v6, 7, v96
	v_lshlrev_b32_e32 v8, 2, v8
	v_or_b32_e32 v98, 16, v94
	v_add3_u32 v97, v3, v6, v8
	v_bitop3_b32 v8, v98, 28, v5 bitop3:0x48
	v_lshlrev_b32_e32 v6, 7, v98
	v_lshlrev_b32_e32 v8, 2, v8
	v_or_b32_e32 v100, 24, v94
	v_add3_u32 v99, v3, v6, v8
	v_bitop3_b32 v8, v100, 28, v5 bitop3:0x48
	v_lshlrev_b32_e32 v6, 7, v100
	v_lshlrev_b32_e32 v8, 2, v8
	v_or_b32_e32 v102, 32, v94
	v_add3_u32 v101, v3, v6, v8
	v_lshlrev_b32_e32 v6, 7, v102
	v_or_b32_e32 v104, 40, v94
	v_add3_u32 v103, v3, v6, v7
	v_bitop3_b32 v7, v104, 28, v5 bitop3:0x48
	v_readlane_b32 s36, v253, 18
	v_lshlrev_b32_e32 v6, 7, v104
	v_lshlrev_b32_e32 v7, 2, v7
	v_or_b32_e32 v106, 48, v94
	v_readlane_b32 s40, v253, 22
	v_readlane_b32 s41, v253, 23
	v_add3_u32 v105, v3, v6, v7
	v_bitop3_b32 v7, v106, 28, v5 bitop3:0x48
	v_or_b32_e32 v108, 56, v94
	v_readlane_b32 s37, v253, 19
	v_readlane_b32 s38, v253, 20
	v_readlane_b32 s39, v253, 21
	v_readlane_b32 s42, v253, 24
	v_readlane_b32 s43, v253, 25
	v_readlane_b32 s44, v253, 26
	v_readlane_b32 s45, v253, 27
	v_readlane_b32 s46, v253, 28
	v_readlane_b32 s47, v253, 29
	v_readlane_b32 s48, v253, 30
	v_readlane_b32 s49, v253, 31
	v_readlane_b32 s50, v253, 32
	v_readlane_b32 s51, v253, 33
	s_cmp_lg_u64 s[40:41], 0
	v_and_b32_e32 v2, 60, v5
	v_lshlrev_b32_e32 v6, 7, v106
	v_lshlrev_b32_e32 v7, 2, v7
	v_bitop3_b32 v5, v108, 28, v5 bitop3:0x48
	s_cselect_b64 s[6:7], -1, 0
	s_cmp_lg_u64 s[44:45], 0
	v_readlane_b32 s36, v253, 2
	v_add3_u32 v107, v3, v6, v7
	v_lshlrev_b32_e32 v6, 7, v108
	v_lshlrev_b32_e32 v5, 2, v5
	v_readlane_b32 s40, v253, 6
	v_readlane_b32 s41, v253, 7
	v_lshlrev_b32_e32 v67, 1, v4
	v_add3_u32 v109, v3, v6, v5
	v_lshlrev_b32_e32 v3, 11, v4
	v_lshlrev_b32_e32 v4, 12, v4
	s_cselect_b64 s[8:9], -1, 0
	v_readlane_b32 s37, v253, 3
	v_readlane_b32 s38, v253, 4
	v_readlane_b32 s39, v253, 5
	s_cmp_lg_u64 s[40:41], 0
	v_lshlrev_b32_e32 v5, 2, v11
	v_readlane_b32 s0, v253, 34
	s_movk_i32 s16, 0xf000
	v_mov_b32_e32 v69, 0
	v_lshlrev_b32_e32 v86, 7, v2
	v_and_b32_e32 v70, 56, v12
	s_cselect_b64 s[12:13], -1, 0
	v_lshl_add_u32 v110, v11, 6, s24
	s_lshl_b32 s11, s10, 6
	v_lshl_add_u32 v111, s0, 5, v5
	s_lshl_b32 s36, s10, 2
	v_mov_b64_e32 v[72:73], s[92:93]
	s_movk_i32 s37, 0x2000
	s_mov_b32 s38, 0x10000
	s_mov_b32 s39, 0x12000
	s_mov_b32 s2, 0x20000
	s_mov_b32 s3, 0x22000
	s_mov_b32 s76, 0x30000
	s_mov_b32 s77, 0x32000
	s_mov_b32 s78, 0x40000
	s_mov_b32 s79, 0x42000
	s_mov_b32 s80, 0x50000
	s_mov_b32 s81, 0x52000
	s_mov_b32 s82, 0x60000
	s_mov_b32 s83, 0x62000
	s_mov_b32 s84, 0x70000
	v_lshlrev_b32_e32 v112, 2, v3
	s_mov_b32 s85, 0x39000
	v_lshlrev_b32_e32 v113, 2, v4
	s_mov_b32 s86, 0x48000
	s_mov_b32 s87, 0x80000
	s_mov_b32 s88, 0x88000
	s_mov_b32 s89, 0xc0000
	s_mov_b32 s56, 0xc8000
	s_mov_b32 s57, 0x100000
	s_mov_b32 s58, 0x108000
	s_mov_b32 s59, 0x140000
	s_mov_b32 s60, 0x148000
	s_mov_b32 s61, 0x180000
	s_mov_b32 s64, 0x1400000
	s_mov_b32 s65, 0x14000
	s_mov_b32 s66, 0x16000
	s_mov_b32 s67, 0x2a000
	s_mov_b32 s68, 0x3c000
	s_mov_b32 s69, 0x3e000
	v_lshlrev_b32_e32 v68, 2, v2
	v_mov_b32_e32 v114, 6
	s_mov_b32 s70, 0x64000
	s_mov_b32 s71, 0x66000
	s_mov_b32 s72, 0x78000
	s_movk_i32 s73, 0xcff
	s_mov_b64 s[14:15], 0
	s_mov_b32 s17, -1
	s_mov_b64 s[18:19], 0xc00000
	s_mov_b64 s[20:21], 0xa00000
	s_mov_b64 s[22:23], 0x3400000
	s_mov_b64 s[24:25], 0x1400000
	v_readlane_b32 s42, v253, 8
	v_readlane_b32 s43, v253, 9
	v_readlane_b32 s44, v253, 10
	v_readlane_b32 s45, v253, 11
	v_readlane_b32 s46, v253, 12
	v_readlane_b32 s47, v253, 13
	v_readlane_b32 s48, v253, 14
	v_readlane_b32 s49, v253, 15
	v_readlane_b32 s50, v253, 16
	v_readlane_b32 s51, v253, 17
	s_branch .LBB0_118

; __device__ __forceinline__ void p0_prologue(const Params& p, LAS unsigned char* lds, int tid) {
;     ...
;     for (int it = gw; it < I_LAYER * DEPTH; it += NGW) {
;         const int l = it / I_LAYER; int r = it % I_LAYER;
;         unsigned char* wl = p.ws + (size_t)l * LAYER_BYTES;
;         if (r < I_IN) { p0_transpose_item(p.in[3] + (size_t)l * DM * INW, DM, INW, p.in[2] + l * DM, nullptr, (bf16_t*)(wl + LO_WIN), scr, r, lane); continue; } r -= I_IN;
;         if (r < I_UP) { p0_transpose_item(p.in[21] + (size_t)l * DM * DFF, DM, DFF, p.in[20] + l * DM, nullptr, (bf16_t*)(wl + LO_WUP), scr, r, lane); continue; } r -= I_UP;
;         if (r < I_DN) { p0_transpose_item(p.in[22] + (size_t)l * DFF * DM, DFF, DM, nullptr, nullptr, (bf16_t*)(wl + LO_WDN), scr, r, lane); continue; } r -= I_DN;
;         if (r < I_GLU) { p0_transpose_item(p.in[15] + (size_t)l * 1024 * 1024, 1024, 1024, nullptr, nullptr, (bf16_t*)(wl + LO_WGLU), scr, r, lane); continue; } r -= I_GLU;
;         p0_transpose_item(p.in[19] + (size_t)l * DM * DM, DM, DM, p.in[17] + l * 1024, p.in[18] + l * 1024, (bf16_t*)(wl + LO_WOUT), scr, r, lane);
;     }
.LBB0_427:
	v_readlane_b32 s98, v254, 36
	v_readlane_b32 s99, v253, 34
	s_cmp_lt_u32 s99, 64
	s_cbranch_scc1 .Lmy_w_skip
	v_writelane_b32 v140, s0, 0
	v_writelane_b32 v140, s1, 1
	v_writelane_b32 v140, s2, 2
	v_writelane_b32 v140, s3, 3
	v_writelane_b32 v140, s4, 4
	v_writelane_b32 v140, s5, 5
	v_writelane_b32 v140, s6, 6
	v_writelane_b32 v140, s7, 7
	v_writelane_b32 v140, s8, 8
	v_writelane_b32 v140, s9, 9
	v_writelane_b32 v140, s10, 10
	v_writelane_b32 v140, s11, 11
	v_writelane_b32 v140, s12, 12
	v_writelane_b32 v140, s13, 13
	v_writelane_b32 v140, s14, 14
	v_writelane_b32 v140, s15, 15
	v_writelane_b32 v140, s16, 16
	v_writelane_b32 v140, s17, 17
	v_writelane_b32 v140, s18, 18
	v_writelane_b32 v140, s19, 19
	v_writelane_b32 v140, s20, 20
	v_writelane_b32 v140, s21, 21
	v_writelane_b32 v140, s22, 22
	v_writelane_b32 v140, s23, 23
	v_writelane_b32 v140, s24, 24
	v_writelane_b32 v140, s25, 25
	v_writelane_b32 v140, s26, 26
	v_writelane_b32 v140, s27, 27
	v_writelane_b32 v140, s28, 28
	v_writelane_b32 v140, s29, 29
	v_writelane_b32 v140, s30, 30
	v_writelane_b32 v140, s31, 31
	v_writelane_b32 v140, s32, 32
	v_writelane_b32 v140, s33, 33
	v_writelane_b32 v140, s34, 34
	v_writelane_b32 v140, s35, 35
	v_writelane_b32 v140, s36, 36
	v_writelane_b32 v140, s37, 37
	v_writelane_b32 v140, s38, 38
	v_writelane_b32 v140, s39, 39
	v_writelane_b32 v140, s40, 40
	v_writelane_b32 v140, s41, 41
	v_writelane_b32 v140, s42, 42
	v_writelane_b32 v140, s43, 43
	v_writelane_b32 v140, s44, 44
	v_writelane_b32 v140, s45, 45
	v_writelane_b32 v140, s46, 46
	v_writelane_b32 v140, s47, 47
	v_writelane_b32 v140, s48, 48
	v_writelane_b32 v140, s49, 49
	v_writelane_b32 v140, s50, 50
	v_writelane_b32 v140, s51, 51
	v_writelane_b32 v140, s52, 52
	v_writelane_b32 v140, s53, 53
	v_writelane_b32 v140, s54, 54
	v_writelane_b32 v140, s55, 55
	v_writelane_b32 v140, s56, 56
	v_writelane_b32 v140, s57, 57
	v_writelane_b32 v140, s58, 58
	v_writelane_b32 v140, s59, 59
	v_writelane_b32 v140, s60, 60
	v_writelane_b32 v140, s61, 61
	v_writelane_b32 v140, s62, 62
	v_writelane_b32 v140, s63, 63
	v_writelane_b32 v141, s64, 0
	v_writelane_b32 v141, s65, 1
	v_writelane_b32 v141, s66, 2
	v_writelane_b32 v141, s67, 3
	v_writelane_b32 v141, s68, 4
	v_writelane_b32 v141, s69, 5
	v_writelane_b32 v141, s70, 6
	v_writelane_b32 v141, s71, 7
	v_writelane_b32 v141, s72, 8
	v_writelane_b32 v141, s73, 9
	v_writelane_b32 v141, s74, 10
	v_writelane_b32 v141, s75, 11
	v_writelane_b32 v141, s76, 12
	v_writelane_b32 v141, s77, 13
	v_writelane_b32 v141, s78, 14
	v_writelane_b32 v141, s79, 15
	v_writelane_b32 v141, s80, 16
	v_writelane_b32 v141, s81, 17
	v_writelane_b32 v141, s82, 18
	v_writelane_b32 v141, s83, 19
	v_writelane_b32 v141, s84, 20
	v_writelane_b32 v141, s85, 21
	v_writelane_b32 v141, s86, 22
	v_writelane_b32 v141, s87, 23
	v_writelane_b32 v141, s88, 24
	v_writelane_b32 v141, s89, 25
	v_writelane_b32 v141, s90, 26
	v_writelane_b32 v141, s91, 27
	v_writelane_b32 v141, s92, 28
	v_writelane_b32 v141, s93, 29
	v_writelane_b32 v141, s94, 30
	v_writelane_b32 v141, s95, 31
	v_writelane_b32 v141, s96, 32
	v_writelane_b32 v141, s97, 33
	s_mul_i32 s98, s98, 0x2a00
	s_add_i32 s0, s98, 0xd00
	s_add_i32 s98, s0, 0x2a00
	s_min_u32 s98, s98, 0xa800
	s_sub_i32 s1, s99, 64
	s_lshl_b32 s1, s1, 3
	s_add_i32 s0, s0, s1
	v_and_b32_e32 v34, 63, v201
	v_lshrrev_b32_e32 v35, 6, v201
	v_lshlrev_b32_e32 v36, 3, v201
	v_add_u32_e32 v90, s0, v35
	s_add_i32 s99, s98, -1
	s_sub_i32 s10, s94, 64
	s_lshl_b32 s10, s10, 3
	v_readlane_b32 s62, v255, 8
	v_readlane_b32 s63, v255, 9
	s_branch .Lmy_w_entry
